# gate/up GEMM epilogue: hidden-activation stores written through (sc0 sc1)
# speedup vs baseline: 1.0008x; 1.0008x over previous
; #define PG8_STAGE(bufoff, gbase, voff) do { _Pragma("unroll") for (int _i = 0; _i < 2; ++_i) \
;         __builtin_amdgcn_global_load_lds((const unsigned*)((const char*)(gbase) + (voff)[_i]), (PG8_LAS unsigned*)(lds + (bufoff) + ldsw + _i * 8192), 16, 0, 0); } while (0)
; #define PG8_LDA(dst, b, h) do { int aoff; asm volatile("v_add_u32 %0, %1, %2" : "=v"(aoff) : "s"(ua), "v"(foff)); _Pragma("unroll") for (int m = 0; m < 4; ++m) _Pragma("unroll") for (int k = 0; k < 2; ++k) dst[m][k] = *(const PG8_LAS bf16x8*)(lds + PG8_SA(b, h) + aoff + m * 2048 + k * 1024); } while (0)
; #define PG8_LDB(dst, b, h) do { int boff; asm volatile("v_add_u32 %0, %1, %2" : "=v"(boff) : "s"(ub), "v"(foff)); _Pragma("unroll") for (int n = 0; n < 2; ++n) _Pragma("unroll") for (int k = 0; k < 2; ++k) dst[n][k] = *(const PG8_LAS bf16x8*)(lds + PG8_SB(b, h) + boff + n * 2048 + k * 1024); } while (0)
; #define PG8_WAIT_V(n) asm volatile("s_waitcnt vmcnt(" #n ")" ::: "memory")
; template <class Epi, class Sched>
; __device__ __forceinline__ void gemm_phase(PG8_LAS unsigned char* lds, const Gemm g, const Sched& S, const Epi& E) {
;     ...
;             PG8_LDB(B0, 0, 0); PG8_SCHED; PG8_LDA(At, 0, 0); PG8_STAGE(PG8_SA(1, 1), a1 + hstep, voffA);
;             PG8_WAIT_L(8); PG8_BAR; PG8_WAIT_L(0); PG8_MMA(0, 0, At, B0); PG8_BAR; PG8_SCHED;
;             PG8_LDB(B1, 0, 1); PG8_STAGE(PG8_SB(0, 0), b2, voffB);
;             PG8_BAR; PG8_WAIT_L(0); PG8_MMA(0, 1, At, B1); PG8_BAR;
;             PG8_LDA(At, 0, 1); PG8_STAGE(PG8_SA(0, 0), a2, voffA);
;             PG8_BAR; PG8_WAIT_L(0); PG8_MMA(1, 0, At, B0); PG8_BAR; PG8_SCHED;
;             PG8_STAGE(PG8_SB(0, 1), b2 + hstep, voffB);
;             PG8_WAIT_V(6); PG8_BAR; PG8_MMA(1, 1, At, B1); PG8_BAR;
;             PG8_LDB(B0, 1, 0); PG8_SCHED; PG8_LDA(At, 1, 0); PG8_STAGE(PG8_SA(0, 1), a2 + hstep, voffA);
;             PG8_WAIT_L(8); PG8_BAR; PG8_WAIT_L(0); PG8_MMA(0, 0, At, B0); PG8_BAR; PG8_SCHED;
;             PG8_LDB(B1, 1, 1); PG8_STAGE(PG8_SB(1, 0), b3, voffB);
;             PG8_BAR; PG8_WAIT_L(0); PG8_MMA(0, 1, At, B1); PG8_BAR;
;             PG8_LDA(At, 1, 1); PG8_STAGE(PG8_SA(1, 0), a3, voffA);
;             PG8_BAR; PG8_WAIT_L(0); PG8_MMA(1, 0, At, B0); PG8_BAR; PG8_SCHED;
;             PG8_STAGE(PG8_SB(1, 1), b3 + hstep, voffB);
;             PG8_WAIT_V(6); PG8_BAR; PG8_MMA(1, 1, At, B1); PG8_BAR;
.LBB0_1109:
	s_add_u32 s44, s26, 0xfffc0080
	s_addc_u32 s45, s27, -1
	s_add_i32 s75, 0, 0x10000
	v_add_u32 v142, s51, v1
	s_cmp_eq_u32 s74, 12
	v_add_u32_e32 v158, s75, v142
	ds_read_b128 v[142:145], v158
	ds_read_b128 v[146:149], v158 offset:1024
	ds_read_b128 v[150:153], v158 offset:2048
	ds_read_b128 v[158:161], v158 offset:3072
	s_cselect_b32 s47, s5, s45
	s_cselect_b32 s46, s21, s44
	s_cselect_b32 s45, s19, s63
	s_cselect_b32 s44, s61, s62
	v_add_u32 v162, s50, v1
	v_lshl_add_u64 v[194:195], s[26:27], 0, v[138:139]
	v_add_u32_e32 v190, 0, v162
	s_add_i32 m0, s3, 0xc000
	ds_read_b128 v[162:165], v190
	ds_read_b128 v[166:169], v190 offset:1024
	ds_read_b128 v[170:173], v190 offset:2048
	ds_read_b128 v[174:177], v190 offset:3072
	ds_read_b128 v[178:181], v190 offset:4096
	ds_read_b128 v[182:185], v190 offset:5120
	ds_read_b128 v[186:189], v190 offset:6144
	ds_read_b128 v[190:193], v190 offset:7168
	global_load_lds_dwordx4 v[194:195], off
	v_lshl_add_u64 v[194:195], s[26:27], 0, v[140:141]
	s_add_i32 m0, s3, 0xe000
	s_nop 0
	global_load_lds_dwordx4 v[194:195], off
	s_waitcnt lgkmcnt(8)
	s_barrier
	s_waitcnt lgkmcnt(0)
	s_setprio 1
	s_waitcnt lgkmcnt(0)
	v_mfma_f32_16x16x32_bf16 v[126:129], v[142:145], v[162:165], v[126:129]
	v_mfma_f32_16x16x32_bf16 v[118:121], v[150:153], v[162:165], v[118:121]
	v_mfma_f32_16x16x32_bf16 v[110:113], v[142:145], v[170:173], v[110:113]
	v_mfma_f32_16x16x32_bf16 v[102:105], v[150:153], v[170:173], v[102:105]
	v_mfma_f32_16x16x32_bf16 v[94:97], v[142:145], v[178:181], v[94:97]
	v_mfma_f32_16x16x32_bf16 v[86:89], v[150:153], v[178:181], v[86:89]
	v_mfma_f32_16x16x32_bf16 v[78:81], v[142:145], v[186:189], v[78:81]
	v_mfma_f32_16x16x32_bf16 v[70:73], v[150:153], v[186:189], v[70:73]
	v_mfma_f32_16x16x32_bf16 v[126:129], v[146:149], v[166:169], v[126:129]
	v_mfma_f32_16x16x32_bf16 v[118:121], v[158:161], v[166:169], v[118:121]
	v_mfma_f32_16x16x32_bf16 v[110:113], v[146:149], v[174:177], v[110:113]
	v_mfma_f32_16x16x32_bf16 v[102:105], v[158:161], v[174:177], v[102:105]
	v_mfma_f32_16x16x32_bf16 v[94:97], v[146:149], v[182:185], v[94:97]
	v_mfma_f32_16x16x32_bf16 v[86:89], v[158:161], v[182:185], v[86:89]
	v_mfma_f32_16x16x32_bf16 v[78:81], v[146:149], v[190:193], v[78:81]
	v_mfma_f32_16x16x32_bf16 v[70:73], v[158:161], v[190:193], v[70:73]
	s_setprio 0
	s_barrier
	s_add_i32 s78, 0, 0x14000
	s_add_i32 s75, s75, s11
	v_add_u32 v194, s51, v1
	v_lshl_add_u64 v[212:213], s[44:45], 0, v[134:135]
	v_add_u32_e32 v206, s78, v194
	s_mov_b32 m0, s75
	ds_read_b128 v[194:197], v206
	ds_read_b128 v[198:201], v206 offset:1024
	ds_read_b128 v[202:205], v206 offset:2048
	ds_read_b128 v[206:209], v206 offset:3072
	global_load_lds_dwordx4 v[212:213], off
	v_lshl_add_u64 v[214:215], s[44:45], 0, v[130:131]
	s_add_i32 m0, s75, 0x2000
	s_nop 0
	global_load_lds_dwordx4 v[214:215], off
	s_barrier
	s_waitcnt lgkmcnt(0)
	s_setprio 1
	s_waitcnt lgkmcnt(0)
	v_mfma_f32_16x16x32_bf16 v[122:125], v[194:197], v[162:165], v[122:125]
	v_mfma_f32_16x16x32_bf16 v[114:117], v[202:205], v[162:165], v[114:117]
	v_mfma_f32_16x16x32_bf16 v[106:109], v[194:197], v[170:173], v[106:109]
	v_mfma_f32_16x16x32_bf16 v[98:101], v[202:205], v[170:173], v[98:101]
	v_mfma_f32_16x16x32_bf16 v[90:93], v[194:197], v[178:181], v[90:93]
	v_mfma_f32_16x16x32_bf16 v[82:85], v[202:205], v[178:181], v[82:85]
	v_mfma_f32_16x16x32_bf16 v[74:77], v[194:197], v[186:189], v[74:77]
	v_mfma_f32_16x16x32_bf16 v[66:69], v[202:205], v[186:189], v[66:69]
	v_mfma_f32_16x16x32_bf16 v[122:125], v[198:201], v[166:169], v[122:125]
	v_mfma_f32_16x16x32_bf16 v[114:117], v[206:209], v[166:169], v[114:117]
	v_mfma_f32_16x16x32_bf16 v[106:109], v[198:201], v[174:177], v[106:109]
	v_mfma_f32_16x16x32_bf16 v[98:101], v[206:209], v[174:177], v[98:101]
	v_mfma_f32_16x16x32_bf16 v[90:93], v[198:201], v[182:185], v[90:93]
	v_mfma_f32_16x16x32_bf16 v[82:85], v[206:209], v[182:185], v[82:85]
	v_mfma_f32_16x16x32_bf16 v[74:77], v[198:201], v[190:193], v[74:77]
	v_mfma_f32_16x16x32_bf16 v[66:69], v[206:209], v[190:193], v[66:69]
	s_setprio 0
	s_mov_b32 m0, s3
	s_barrier
	v_add_u32 v162, s50, v1
	v_lshl_add_u64 v[218:219], s[46:47], 0, v[136:137]
	v_add_u32_e32 v190, 0, v162
	ds_read_b128 v[162:165], v190 offset:16384
	ds_read_b128 v[166:169], v190 offset:17408
	ds_read_b128 v[170:173], v190 offset:18432
	ds_read_b128 v[174:177], v190 offset:19456
	ds_read_b128 v[178:181], v190 offset:20480
	ds_read_b128 v[182:185], v190 offset:21504
	ds_read_b128 v[186:189], v190 offset:22528
	ds_read_b128 v[190:193], v190 offset:23552
	global_load_lds_dwordx4 v[218:219], off
	v_lshl_add_u64 v[220:221], s[46:47], 0, v[132:133]
	s_mov_b32 m0, s17
	s_nop 0
	global_load_lds_dwordx4 v[220:221], off
	s_barrier
	s_waitcnt lgkmcnt(0)
	s_setprio 1
	s_waitcnt lgkmcnt(0)
	v_mfma_f32_16x16x32_bf16 v[62:65], v[142:145], v[162:165], v[62:65]
	v_mfma_f32_16x16x32_bf16 v[54:57], v[150:153], v[162:165], v[54:57]
	v_mfma_f32_16x16x32_bf16 v[46:49], v[142:145], v[170:173], v[46:49]
	v_mfma_f32_16x16x32_bf16 v[38:41], v[150:153], v[170:173], v[38:41]
	v_mfma_f32_16x16x32_bf16 v[30:33], v[142:145], v[178:181], v[30:33]
	v_mfma_f32_16x16x32_bf16 v[22:25], v[150:153], v[178:181], v[22:25]
	v_mfma_f32_16x16x32_bf16 v[14:17], v[142:145], v[186:189], v[14:17]
	v_mfma_f32_16x16x32_bf16 v[6:9], v[150:153], v[186:189], v[6:9]
	v_mfma_f32_16x16x32_bf16 v[62:65], v[146:149], v[166:169], v[62:65]
	v_mfma_f32_16x16x32_bf16 v[54:57], v[158:161], v[166:169], v[54:57]
	v_mfma_f32_16x16x32_bf16 v[46:49], v[146:149], v[174:177], v[46:49]
	v_mfma_f32_16x16x32_bf16 v[38:41], v[158:161], v[174:177], v[38:41]
	v_mfma_f32_16x16x32_bf16 v[30:33], v[146:149], v[182:185], v[30:33]
	v_mfma_f32_16x16x32_bf16 v[22:25], v[158:161], v[182:185], v[22:25]
	v_mfma_f32_16x16x32_bf16 v[14:17], v[146:149], v[190:193], v[14:17]
	v_mfma_f32_16x16x32_bf16 v[6:9], v[158:161], v[190:193], v[6:9]
	s_setprio 0
	s_barrier
; #define PG8_STAGE(bufoff, gbase, voff) do { _Pragma("unroll") for (int _i = 0; _i < 2; ++_i) \
;         __builtin_amdgcn_global_load_lds((const unsigned*)((const char*)(gbase) + (voff)[_i]), (PG8_LAS unsigned*)(lds + (bufoff) + ldsw + _i * 8192), 16, 0, 0); } while (0)
; #define PG8_LDA(dst, b, h) do { int aoff; asm volatile("v_add_u32 %0, %1, %2" : "=v"(aoff) : "s"(ua), "v"(foff)); _Pragma("unroll") for (int m = 0; m < 4; ++m) _Pragma("unroll") for (int k = 0; k < 2; ++k) dst[m][k] = *(const PG8_LAS bf16x8*)(lds + PG8_SA(b, h) + aoff + m * 2048 + k * 1024); } while (0)
; #define PG8_LDB(dst, b, h) do { int boff; asm volatile("v_add_u32 %0, %1, %2" : "=v"(boff) : "s"(ub), "v"(foff)); _Pragma("unroll") for (int n = 0; n < 2; ++n) _Pragma("unroll") for (int k = 0; k < 2; ++k) dst[n][k] = *(const PG8_LAS bf16x8*)(lds + PG8_SB(b, h) + boff + n * 2048 + k * 1024); } while (0)
; #define PG8_MMA(ai, bj, At, Bt) do { __builtin_amdgcn_s_setprio(1); _Pragma("unroll") for (int m = 0; m < 4; ++m) _Pragma("unroll") for (int n = 0; n < 2; ++n) _Pragma("unroll") for (int k = 0; k < 2; ++k) \
;         acc[ai][bj][m][n] = __builtin_amdgcn_mfma_f32_16x16x32_bf16(Bt[n][k], At[m][k], acc[ai][bj][m][n], 0, 0, 0); __builtin_amdgcn_s_setprio(0); } while (0)
; #define PG8_WAIT_V(n) asm volatile("s_waitcnt vmcnt(" #n ")" ::: "memory")
; #define PG8_WAIT_L(n) asm volatile("s_waitcnt lgkmcnt(" #n ")" ::: "memory")
; #define PG8_BAR __builtin_amdgcn_s_barrier()
; #define PG8_SCHED __builtin_amdgcn_sched_barrier(0)
; template <class Epi, class Sched>
; __device__ __forceinline__ void gemm_phase(PG8_LAS unsigned char* lds, const Gemm g, const Sched& S, const Epi& E) {
;     ...
;             PG8_WAIT_V(6); PG8_BAR; PG8_MMA(1, 1, At, B1); PG8_BAR;
;             PG8_LDB(B0, 1, 0); PG8_SCHED; PG8_LDA(At, 1, 0); PG8_STAGE(PG8_SA(0, 1), a2 + hstep, voffA);
;             PG8_WAIT_L(8); PG8_BAR; PG8_WAIT_L(0); PG8_MMA(0, 0, At, B0); PG8_BAR; PG8_SCHED;
;             PG8_LDB(B1, 1, 1); PG8_STAGE(PG8_SB(1, 0), b3, voffB);
;             PG8_BAR; PG8_WAIT_L(0); PG8_MMA(0, 1, At, B1); PG8_BAR;
;             PG8_LDA(At, 1, 1); PG8_STAGE(PG8_SA(1, 0), a3, voffA);
;             PG8_BAR; PG8_WAIT_L(0); PG8_MMA(1, 0, At, B0); PG8_BAR; PG8_SCHED;
	s_add_u32 s76, s44, 0x40000
	s_addc_u32 s77, s45, 0
	s_add_i32 s75, s78, s11
	v_lshl_add_u64 v[142:143], s[76:77], 0, v[134:135]
	s_mov_b32 m0, s75
	s_nop 0
	global_load_lds_dwordx4 v[142:143], off
	v_lshl_add_u64 v[142:143], s[76:77], 0, v[130:131]
	s_add_i32 m0, s75, 0x2000
	s_nop 0
	global_load_lds_dwordx4 v[142:143], off
	s_waitcnt vmcnt(6)
	s_barrier
	s_setprio 1
	v_mfma_f32_16x16x32_bf16 v[58:61], v[194:197], v[162:165], v[58:61]
	v_mfma_f32_16x16x32_bf16 v[50:53], v[202:205], v[162:165], v[50:53]
	v_mfma_f32_16x16x32_bf16 v[42:45], v[194:197], v[170:173], v[42:45]
	v_mfma_f32_16x16x32_bf16 v[34:37], v[202:205], v[170:173], v[34:37]
	v_mfma_f32_16x16x32_bf16 v[26:29], v[194:197], v[178:181], v[26:29]
	v_mfma_f32_16x16x32_bf16 v[18:21], v[202:205], v[178:181], v[18:21]
	v_mfma_f32_16x16x32_bf16 v[10:13], v[194:197], v[186:189], v[10:13]
	v_mfma_f32_16x16x32_bf16 v[2:5], v[202:205], v[186:189], v[2:5]
	v_mfma_f32_16x16x32_bf16 v[58:61], v[198:201], v[166:169], v[58:61]
	v_mfma_f32_16x16x32_bf16 v[50:53], v[206:209], v[166:169], v[50:53]
	v_mfma_f32_16x16x32_bf16 v[42:45], v[198:201], v[174:177], v[42:45]
	v_mfma_f32_16x16x32_bf16 v[34:37], v[206:209], v[174:177], v[34:37]
	v_mfma_f32_16x16x32_bf16 v[26:29], v[198:201], v[182:185], v[26:29]
	v_mfma_f32_16x16x32_bf16 v[18:21], v[206:209], v[182:185], v[18:21]
	v_mfma_f32_16x16x32_bf16 v[10:13], v[198:201], v[190:193], v[10:13]
	v_mfma_f32_16x16x32_bf16 v[2:5], v[206:209], v[190:193], v[2:5]
	s_setprio 0
	s_add_i32 s75, 0, 0x18000
	s_barrier
	v_add_u32 v142, s51, v1
	s_nop 0
	v_add_u32_e32 v158, s75, v142
	ds_read_b128 v[142:145], v158
	ds_read_b128 v[146:149], v158 offset:1024
	ds_read_b128 v[150:153], v158 offset:2048
	ds_read_b128 v[158:161], v158 offset:3072
	s_add_u32 s46, s46, 0x40000
	s_addc_u32 s47, s47, 0
	s_mov_b32 m0, s48
	v_add_u32 v162, s50, v1
	v_lshl_add_u64 v[194:195], s[46:47], 0, v[136:137]
	v_add_u32_e32 v190, 0, v162
	ds_read_b128 v[162:165], v190 offset:32768
	ds_read_b128 v[166:169], v190 offset:33792
	ds_read_b128 v[170:173], v190 offset:34816
	ds_read_b128 v[174:177], v190 offset:35840
	ds_read_b128 v[178:181], v190 offset:36864
	ds_read_b128 v[182:185], v190 offset:37888
	ds_read_b128 v[186:189], v190 offset:38912
	ds_read_b128 v[190:193], v190 offset:39936
	global_load_lds_dwordx4 v[194:195], off
	v_lshl_add_u64 v[194:195], s[46:47], 0, v[132:133]
	s_mov_b32 m0, s49
	s_nop 0
	global_load_lds_dwordx4 v[194:195], off
	s_waitcnt lgkmcnt(8)
	s_barrier
	s_waitcnt lgkmcnt(0)
	s_setprio 1
	s_waitcnt lgkmcnt(0)
	v_mfma_f32_16x16x32_bf16 v[126:129], v[142:145], v[162:165], v[126:129]
	v_mfma_f32_16x16x32_bf16 v[118:121], v[150:153], v[162:165], v[118:121]
	v_mfma_f32_16x16x32_bf16 v[110:113], v[142:145], v[170:173], v[110:113]
	v_mfma_f32_16x16x32_bf16 v[102:105], v[150:153], v[170:173], v[102:105]
	v_mfma_f32_16x16x32_bf16 v[94:97], v[142:145], v[178:181], v[94:97]
	v_mfma_f32_16x16x32_bf16 v[86:89], v[150:153], v[178:181], v[86:89]
	v_mfma_f32_16x16x32_bf16 v[78:81], v[142:145], v[186:189], v[78:81]
	v_mfma_f32_16x16x32_bf16 v[70:73], v[150:153], v[186:189], v[70:73]
	v_mfma_f32_16x16x32_bf16 v[126:129], v[146:149], v[166:169], v[126:129]
	v_mfma_f32_16x16x32_bf16 v[118:121], v[158:161], v[166:169], v[118:121]
	v_mfma_f32_16x16x32_bf16 v[110:113], v[146:149], v[174:177], v[110:113]
	v_mfma_f32_16x16x32_bf16 v[102:105], v[158:161], v[174:177], v[102:105]
	v_mfma_f32_16x16x32_bf16 v[94:97], v[146:149], v[182:185], v[94:97]
	v_mfma_f32_16x16x32_bf16 v[86:89], v[158:161], v[182:185], v[86:89]
	v_mfma_f32_16x16x32_bf16 v[78:81], v[146:149], v[190:193], v[78:81]
	v_mfma_f32_16x16x32_bf16 v[70:73], v[158:161], v[190:193], v[70:73]
	s_setprio 0
	s_barrier
	s_add_i32 s46, 0, 0x1c000
	s_add_i32 s47, s75, s11
	v_add_u32 v194, s51, v1
	v_lshl_add_u64 v[212:213], v[212:213], 0, s[30:31]
	v_add_u32_e32 v206, s46, v194
	s_mov_b32 m0, s47
	ds_read_b128 v[194:197], v206
	ds_read_b128 v[198:201], v206 offset:1024
	ds_read_b128 v[202:205], v206 offset:2048
	ds_read_b128 v[206:209], v206 offset:3072
	global_load_lds_dwordx4 v[212:213], off
	v_lshl_add_u64 v[212:213], v[214:215], 0, s[30:31]
	s_add_i32 m0, s47, 0x2000
	s_nop 0
	global_load_lds_dwordx4 v[212:213], off
	s_barrier
	s_waitcnt lgkmcnt(0)
	s_setprio 1
	s_waitcnt lgkmcnt(0)
	v_mfma_f32_16x16x32_bf16 v[122:125], v[194:197], v[162:165], v[122:125]
	v_mfma_f32_16x16x32_bf16 v[114:117], v[202:205], v[162:165], v[114:117]
	v_mfma_f32_16x16x32_bf16 v[106:109], v[194:197], v[170:173], v[106:109]
	v_mfma_f32_16x16x32_bf16 v[98:101], v[202:205], v[170:173], v[98:101]
	v_mfma_f32_16x16x32_bf16 v[90:93], v[194:197], v[178:181], v[90:93]
	v_mfma_f32_16x16x32_bf16 v[82:85], v[202:205], v[178:181], v[82:85]
	v_mfma_f32_16x16x32_bf16 v[74:77], v[194:197], v[186:189], v[74:77]
	v_mfma_f32_16x16x32_bf16 v[66:69], v[202:205], v[186:189], v[66:69]
	v_mfma_f32_16x16x32_bf16 v[122:125], v[198:201], v[166:169], v[122:125]
	v_mfma_f32_16x16x32_bf16 v[114:117], v[206:209], v[166:169], v[114:117]
	v_mfma_f32_16x16x32_bf16 v[106:109], v[198:201], v[174:177], v[106:109]
	v_mfma_f32_16x16x32_bf16 v[98:101], v[206:209], v[174:177], v[98:101]
	v_mfma_f32_16x16x32_bf16 v[90:93], v[198:201], v[182:185], v[90:93]
	v_mfma_f32_16x16x32_bf16 v[82:85], v[206:209], v[182:185], v[82:85]
	v_mfma_f32_16x16x32_bf16 v[74:77], v[198:201], v[190:193], v[74:77]
	v_mfma_f32_16x16x32_bf16 v[66:69], v[206:209], v[190:193], v[66:69]
	s_setprio 0
	s_mov_b32 m0, s52
	s_barrier
; __device__ __forceinline__ unsigned cvt_pk_bf16(float lo, float hi) { const f32x2c f = {lo, hi}; return __builtin_bit_cast(unsigned, __builtin_convertvector(f, bf16x2c)); }
; __device__ __forceinline__ float silu_f(float g) { return g * __builtin_amdgcn_rcpf(1.0f + __expf(-g)); }
; #define PG8_STAGE(bufoff, gbase, voff) do { _Pragma("unroll") for (int _i = 0; _i < 2; ++_i) \
;         __builtin_amdgcn_global_load_lds((const unsigned*)((const char*)(gbase) + (voff)[_i]), (PG8_LAS unsigned*)(lds + (bufoff) + ldsw + _i * 8192), 16, 0, 0); } while (0)
; #define PG8_LDA(dst, b, h) do { int aoff; asm volatile("v_add_u32 %0, %1, %2" : "=v"(aoff) : "s"(ua), "v"(foff)); _Pragma("unroll") for (int m = 0; m < 4; ++m) _Pragma("unroll") for (int k = 0; k < 2; ++k) dst[m][k] = *(const PG8_LAS bf16x8*)(lds + PG8_SA(b, h) + aoff + m * 2048 + k * 1024); } while (0)
; #define PG8_WAIT_V(n) asm volatile("s_waitcnt vmcnt(" #n ")" ::: "memory")
; #define PG8_WAIT_L(n) asm volatile("s_waitcnt lgkmcnt(" #n ")" ::: "memory")
;     __device__ __forceinline__ void operator()(const f32x4 (&acc)[2][2][4][2], const Unit& u, int wr, int wc, int fr, int fq) const {
;     ...
;             for (int m = 0; m < 4; ++m) { bf16_t* rowp = H + (size_t)(row0 + ai * HALF + m * 16) * ldh + col0;
;                 const f32x4 g0 = acc[ai][0][m][0], g1 = acc[ai][0][m][1], u0 = acc[ai][1][m][0], u1 = acc[ai][1][m][1];
;                 u32x4 w; w.x = cvt_pk_bf16(silu_f(g0[0]) * u0[0], silu_f(g0[1]) * u0[1]); w.y = cvt_pk_bf16(silu_f(g0[2]) * u0[2], silu_f(g0[3]) * u0[3]);
;                 w.z = cvt_pk_bf16(silu_f(g1[0]) * u1[0], silu_f(g1[1]) * u1[1]); w.w = cvt_pk_bf16(silu_f(g1[2]) * u1[2], silu_f(g1[3]) * u1[3]);
; template <class Epi, class Sched>
; __device__ __forceinline__ void gemm_phase(PG8_LAS unsigned char* lds, const Gemm g, const Sched& S, const Epi& E) {
;     ...
;             PG8_WAIT_L(8); PG8_BAR; PG8_WAIT_L(0); PG8_MMA(0, 0, At, B0); PG8_BAR; PG8_SCHED;
;             PG8_LDB(B1, 1, 1); PG8_STAGE(PG8_SB(1, 0), b3, voffB);
;             PG8_BAR; PG8_WAIT_L(0); PG8_MMA(0, 1, At, B1); PG8_BAR;
;             PG8_LDA(At, 1, 1); PG8_STAGE(PG8_SA(1, 0), a3, voffA);
;             PG8_BAR; PG8_WAIT_L(0); PG8_MMA(1, 0, At, B0); PG8_BAR; PG8_SCHED;
;             PG8_STAGE(PG8_SB(1, 1), b3 + hstep, voffB);
;             PG8_WAIT_V(6); PG8_BAR; PG8_MMA(1, 1, At, B1); PG8_BAR;
	v_add_u32 v162, s50, v1
	v_lshl_add_u64 v[212:213], v[218:219], 0, s[30:31]
	v_add_u32_e32 v190, 0, v162
	ds_read_b128 v[162:165], v190 offset:49152
	ds_read_b128 v[166:169], v190 offset:50176
	ds_read_b128 v[170:173], v190 offset:51200
	ds_read_b128 v[174:177], v190 offset:52224
	ds_read_b128 v[178:181], v190 offset:53248
	ds_read_b128 v[182:185], v190 offset:54272
	ds_read_b128 v[186:189], v190 offset:55296
	ds_read_b128 v[190:193], v190 offset:56320
	global_load_lds_dwordx4 v[212:213], off
	v_lshl_add_u64 v[212:213], v[220:221], 0, s[30:31]
	s_mov_b32 m0, s53
	s_nop 0
	global_load_lds_dwordx4 v[212:213], off
	s_barrier
	s_waitcnt lgkmcnt(0)
	s_setprio 1
	s_waitcnt lgkmcnt(0)
	v_mfma_f32_16x16x32_bf16 v[62:65], v[142:145], v[162:165], v[62:65]
	v_mfma_f32_16x16x32_bf16 v[54:57], v[150:153], v[162:165], v[54:57]
	v_mfma_f32_16x16x32_bf16 v[46:49], v[142:145], v[170:173], v[46:49]
	v_mfma_f32_16x16x32_bf16 v[38:41], v[150:153], v[170:173], v[38:41]
	v_mfma_f32_16x16x32_bf16 v[30:33], v[142:145], v[178:181], v[30:33]
	v_mfma_f32_16x16x32_bf16 v[22:25], v[150:153], v[178:181], v[22:25]
	v_mfma_f32_16x16x32_bf16 v[14:17], v[142:145], v[186:189], v[14:17]
	v_mfma_f32_16x16x32_bf16 v[6:9], v[150:153], v[186:189], v[6:9]
	v_mfma_f32_16x16x32_bf16 v[62:65], v[146:149], v[166:169], v[62:65]
	v_mfma_f32_16x16x32_bf16 v[54:57], v[158:161], v[166:169], v[54:57]
	v_mfma_f32_16x16x32_bf16 v[46:49], v[146:149], v[174:177], v[46:49]
	v_mfma_f32_16x16x32_bf16 v[38:41], v[158:161], v[174:177], v[38:41]
	v_mfma_f32_16x16x32_bf16 v[30:33], v[146:149], v[182:185], v[30:33]
	v_mfma_f32_16x16x32_bf16 v[22:25], v[158:161], v[182:185], v[22:25]
	v_mfma_f32_16x16x32_bf16 v[14:17], v[146:149], v[190:193], v[14:17]
	v_mfma_f32_16x16x32_bf16 v[6:9], v[158:161], v[190:193], v[6:9]
	s_setprio 0
	s_barrier
	s_add_u32 s44, s44, 0x40080
	s_addc_u32 s45, s45, 0
	s_add_i32 s46, s46, s11
	v_lshl_add_u64 v[142:143], s[44:45], 0, v[134:135]
	s_mov_b32 m0, s46
	s_nop 0
	global_load_lds_dwordx4 v[142:143], off
	v_lshl_add_u64 v[142:143], s[44:45], 0, v[130:131]
	s_add_i32 m0, s46, 0x2000
	s_nop 0
	global_load_lds_dwordx4 v[142:143], off
	s_waitcnt vmcnt(6)
	s_barrier
	s_setprio 1
	v_mfma_f32_16x16x32_bf16 v[58:61], v[194:197], v[162:165], v[58:61]
	v_mfma_f32_16x16x32_bf16 v[50:53], v[202:205], v[162:165], v[50:53]
	v_mfma_f32_16x16x32_bf16 v[42:45], v[194:197], v[170:173], v[42:45]
	v_mfma_f32_16x16x32_bf16 v[34:37], v[202:205], v[170:173], v[34:37]
	v_mfma_f32_16x16x32_bf16 v[26:29], v[194:197], v[178:181], v[26:29]
	v_mfma_f32_16x16x32_bf16 v[18:21], v[202:205], v[178:181], v[18:21]
	v_mfma_f32_16x16x32_bf16 v[10:13], v[194:197], v[186:189], v[10:13]
	v_mfma_f32_16x16x32_bf16 v[2:5], v[202:205], v[186:189], v[2:5]
	v_mfma_f32_16x16x32_bf16 v[58:61], v[198:201], v[166:169], v[58:61]
	v_mfma_f32_16x16x32_bf16 v[50:53], v[206:209], v[166:169], v[50:53]
	v_mfma_f32_16x16x32_bf16 v[42:45], v[198:201], v[174:177], v[42:45]
	v_mfma_f32_16x16x32_bf16 v[34:37], v[206:209], v[174:177], v[34:37]
	v_mfma_f32_16x16x32_bf16 v[26:29], v[198:201], v[182:185], v[26:29]
	v_mfma_f32_16x16x32_bf16 v[18:21], v[206:209], v[182:185], v[18:21]
	v_mfma_f32_16x16x32_bf16 v[10:13], v[198:201], v[190:193], v[10:13]
	v_mfma_f32_16x16x32_bf16 v[2:5], v[206:209], v[190:193], v[2:5]
	s_setprio 0
	s_add_i32 s74, s74, 2
	s_add_u32 s26, s26, 0x100
	s_addc_u32 s27, s27, 0
	s_add_u32 s62, s62, 0x100
	s_addc_u32 s63, s63, 0
	s_cmp_gt_u32 s74, 13
	s_barrier
	s_cbranch_scc0 .LBB0_1109
	v_mul_f32_e32 v148, 0xbfb8aa3b, v126
	v_mul_f32_e32 v149, 0xbfb8aa3b, v127
	v_exp_f32_e32 v148, v148
	v_exp_f32_e32 v149, v149
	v_lshl_add_u32 v158, s16, 8, v156
	v_lshl_or_b32 v144, s2, 7, v157
	v_add_f32_e32 v148, 1.0, v148
	v_add_f32_e32 v149, 1.0, v149
	v_rcp_f32_e32 v148, v148
	v_rcp_f32_e32 v149, v149
	v_ashrrev_i32_e32 v145, 31, v144
	v_mov_b64_e32 v[142:143], s[68:69]
	s_movk_i32 s2, 0x1600
	v_pk_mul_f32 v[126:127], v[126:127], v[148:149]
	v_mad_i64_i32 v[146:147], s[26:27], v158, s2, v[142:143]
	v_pk_mul_f32 v[122:123], v[126:127], v[122:123]
	v_lshlrev_b64 v[144:145], 1, v[144:145]
	v_cvt_pk_bf16_f32 v122, v122, v123
	v_mul_f32_e32 v123, 0xbfb8aa3b, v128
	v_exp_f32_e32 v123, v123
	v_lshl_add_u64 v[146:147], v[146:147], 0, v[144:145]
	s_and_b64 vcc, exec, s[38:39]
	s_mov_b32 s16, s20
	v_add_f32_e32 v123, 1.0, v123
	v_rcp_f32_e32 v126, v123
	v_mul_f32_e32 v123, 0xbfb8aa3b, v129
	v_exp_f32_e32 v123, v123
	s_mov_b64 s[44:45], s[28:29]
	v_add_f32_e32 v123, 1.0, v123
	v_rcp_f32_e32 v127, v123
	s_nop 0
	v_pk_mul_f32 v[126:127], v[128:129], v[126:127]
	s_nop 0
	v_pk_mul_f32 v[124:125], v[126:127], v[124:125]
	s_nop 0
	v_cvt_pk_bf16_f32 v123, v124, v125
	v_mul_f32_e32 v124, 0xbfb8aa3b, v118
	v_mul_f32_e32 v125, 0xbfb8aa3b, v119
	v_exp_f32_e32 v124, v124
	v_exp_f32_e32 v125, v125
	v_add_f32_e32 v124, 1.0, v124
	v_add_f32_e32 v125, 1.0, v125
	v_rcp_f32_e32 v124, v124
	v_rcp_f32_e32 v125, v125
	s_nop 0
	v_pk_mul_f32 v[118:119], v[118:119], v[124:125]
	s_nop 0
	v_pk_mul_f32 v[114:115], v[118:119], v[114:115]
	s_nop 0
	v_cvt_pk_bf16_f32 v124, v114, v115
	v_mul_f32_e32 v114, 0xbfb8aa3b, v120
	v_mul_f32_e32 v115, 0xbfb8aa3b, v121
	v_exp_f32_e32 v114, v114
	v_exp_f32_e32 v115, v115
	v_add_f32_e32 v114, 1.0, v114
	v_add_f32_e32 v115, 1.0, v115
	v_rcp_f32_e32 v114, v114
	v_rcp_f32_e32 v115, v115
	s_nop 0
	v_pk_mul_f32 v[114:115], v[120:121], v[114:115]
	s_nop 0
	v_pk_mul_f32 v[114:115], v[114:115], v[116:117]
	v_mul_f32_e32 v116, 0xbfb8aa3b, v110
	v_mul_f32_e32 v117, 0xbfb8aa3b, v111
	v_exp_f32_e32 v116, v116
	v_exp_f32_e32 v117, v117
	v_cvt_pk_bf16_f32 v125, v114, v115
	v_or_b32_e32 v114, 16, v158
	v_add_f32_e32 v116, 1.0, v116
; __device__ __forceinline__ unsigned cvt_pk_bf16(float lo, float hi) { const f32x2c f = {lo, hi}; return __builtin_bit_cast(unsigned, __builtin_convertvector(f, bf16x2c)); }
; __device__ __forceinline__ float silu_f(float g) { return g * __builtin_amdgcn_rcpf(1.0f + __expf(-g)); }
;     __device__ __forceinline__ void operator()(const f32x4 (&acc)[2][2][4][2], const Unit& u, int wr, int wc, int fr, int fq) const {
;         const int row0 = u.pm * BM + wr * 64 + fr; const int col0 = u.pn * HALF + wc * 32 + 8 * fq;
; #pragma unroll
;         for (int ai = 0; ai < 2; ++ai)
; #pragma unroll
;             for (int m = 0; m < 4; ++m) { bf16_t* rowp = H + (size_t)(row0 + ai * HALF + m * 16) * ldh + col0;
;                 const f32x4 g0 = acc[ai][0][m][0], g1 = acc[ai][0][m][1], u0 = acc[ai][1][m][0], u1 = acc[ai][1][m][1];
;                 u32x4 w; w.x = cvt_pk_bf16(silu_f(g0[0]) * u0[0], silu_f(g0[1]) * u0[1]); w.y = cvt_pk_bf16(silu_f(g0[2]) * u0[2], silu_f(g0[3]) * u0[3]);
;                 w.z = cvt_pk_bf16(silu_f(g1[0]) * u1[0], silu_f(g1[1]) * u1[1]); w.w = cvt_pk_bf16(silu_f(g1[2]) * u1[2], silu_f(g1[3]) * u1[3]);
;                 *(u32x4*)rowp = w; }
	v_add_f32_e32 v117, 1.0, v117
	v_rcp_f32_e32 v116, v116
	v_rcp_f32_e32 v117, v117
	v_mad_i64_i32 v[114:115], s[26:27], v114, s2, v[142:143]
	v_lshl_add_u64 v[114:115], v[114:115], 0, v[144:145]
	v_pk_mul_f32 v[110:111], v[110:111], v[116:117]
	global_store_dwordx4 v[146:147], v[122:125], off sc0 sc1
	v_pk_mul_f32 v[106:107], v[110:111], v[106:107]
	s_nop 0
	v_cvt_pk_bf16_f32 v106, v106, v107
	v_mul_f32_e32 v107, 0xbfb8aa3b, v112
	v_exp_f32_e32 v107, v107
	s_nop 0
	v_add_f32_e32 v107, 1.0, v107
	v_rcp_f32_e32 v110, v107
	v_mul_f32_e32 v107, 0xbfb8aa3b, v113
	v_exp_f32_e32 v107, v107
	s_nop 0
	v_add_f32_e32 v107, 1.0, v107
	v_rcp_f32_e32 v111, v107
	s_nop 0
	v_pk_mul_f32 v[110:111], v[112:113], v[110:111]
	s_nop 0
	v_pk_mul_f32 v[108:109], v[110:111], v[108:109]
	s_nop 0
	v_cvt_pk_bf16_f32 v107, v108, v109
	v_mul_f32_e32 v108, 0xbfb8aa3b, v102
	v_mul_f32_e32 v109, 0xbfb8aa3b, v103
	v_exp_f32_e32 v108, v108
	v_exp_f32_e32 v109, v109
	v_add_f32_e32 v108, 1.0, v108
	v_add_f32_e32 v109, 1.0, v109
	v_rcp_f32_e32 v108, v108
	v_rcp_f32_e32 v109, v109
	s_nop 0
	v_pk_mul_f32 v[102:103], v[102:103], v[108:109]
	s_nop 0
	v_pk_mul_f32 v[98:99], v[102:103], v[98:99]
	s_nop 0
	v_cvt_pk_bf16_f32 v108, v98, v99
	v_mul_f32_e32 v98, 0xbfb8aa3b, v104
	v_mul_f32_e32 v99, 0xbfb8aa3b, v105
	v_exp_f32_e32 v98, v98
	v_exp_f32_e32 v99, v99
	v_add_f32_e32 v98, 1.0, v98
	v_add_f32_e32 v99, 1.0, v99
	v_rcp_f32_e32 v98, v98
	v_rcp_f32_e32 v99, v99
	s_nop 0
	v_pk_mul_f32 v[98:99], v[104:105], v[98:99]
	s_nop 0
	v_pk_mul_f32 v[98:99], v[98:99], v[100:101]
	v_mul_f32_e32 v100, 0xbfb8aa3b, v94
	v_mul_f32_e32 v101, 0xbfb8aa3b, v95
	v_exp_f32_e32 v100, v100
	v_exp_f32_e32 v101, v101
	v_cvt_pk_bf16_f32 v109, v98, v99
	v_or_b32_e32 v98, 32, v158
	v_add_f32_e32 v100, 1.0, v100
	v_add_f32_e32 v101, 1.0, v101
	v_rcp_f32_e32 v100, v100
	v_rcp_f32_e32 v101, v101
	v_mad_i64_i32 v[98:99], s[26:27], v98, s2, v[142:143]
	v_lshl_add_u64 v[98:99], v[98:99], 0, v[144:145]
	v_pk_mul_f32 v[94:95], v[94:95], v[100:101]
	global_store_dwordx4 v[114:115], v[106:109], off sc0 sc1
	v_pk_mul_f32 v[90:91], v[94:95], v[90:91]
	s_nop 0
	v_cvt_pk_bf16_f32 v90, v90, v91
	v_mul_f32_e32 v91, 0xbfb8aa3b, v96
	v_exp_f32_e32 v91, v91
	s_nop 0
	v_add_f32_e32 v91, 1.0, v91
	v_rcp_f32_e32 v94, v91
	v_mul_f32_e32 v91, 0xbfb8aa3b, v97
	v_exp_f32_e32 v91, v91
	s_nop 0
	v_add_f32_e32 v91, 1.0, v91
	v_rcp_f32_e32 v95, v91
	s_nop 0
	v_pk_mul_f32 v[94:95], v[96:97], v[94:95]
	s_nop 0
	v_pk_mul_f32 v[92:93], v[94:95], v[92:93]
	s_nop 0
	v_cvt_pk_bf16_f32 v91, v92, v93
	v_mul_f32_e32 v92, 0xbfb8aa3b, v86
	v_mul_f32_e32 v93, 0xbfb8aa3b, v87
	v_exp_f32_e32 v92, v92
	v_exp_f32_e32 v93, v93
	v_add_f32_e32 v92, 1.0, v92
	v_add_f32_e32 v93, 1.0, v93
	v_rcp_f32_e32 v92, v92
	v_rcp_f32_e32 v93, v93
	s_nop 0
	v_pk_mul_f32 v[86:87], v[86:87], v[92:93]
	s_nop 0
	v_pk_mul_f32 v[82:83], v[86:87], v[82:83]
	s_nop 0
	v_cvt_pk_bf16_f32 v92, v82, v83
	v_mul_f32_e32 v82, 0xbfb8aa3b, v88
	v_mul_f32_e32 v83, 0xbfb8aa3b, v89
	v_exp_f32_e32 v82, v82
	v_exp_f32_e32 v83, v83
	v_add_f32_e32 v82, 1.0, v82
	v_add_f32_e32 v83, 1.0, v83
	v_rcp_f32_e32 v82, v82
	v_rcp_f32_e32 v83, v83
	s_nop 0
	v_pk_mul_f32 v[82:83], v[88:89], v[82:83]
	s_nop 0
	v_pk_mul_f32 v[82:83], v[82:83], v[84:85]
	v_mul_f32_e32 v84, 0xbfb8aa3b, v78
	v_mul_f32_e32 v85, 0xbfb8aa3b, v79
	v_exp_f32_e32 v84, v84
	v_exp_f32_e32 v85, v85
	v_cvt_pk_bf16_f32 v93, v82, v83
	v_or_b32_e32 v82, 48, v158
	v_add_f32_e32 v84, 1.0, v84
	v_add_f32_e32 v85, 1.0, v85
	v_rcp_f32_e32 v84, v84
	v_rcp_f32_e32 v85, v85
	v_mad_i64_i32 v[82:83], s[26:27], v82, s2, v[142:143]
	v_lshl_add_u64 v[82:83], v[82:83], 0, v[144:145]
	v_pk_mul_f32 v[78:79], v[78:79], v[84:85]
	global_store_dwordx4 v[98:99], v[90:93], off sc0 sc1
	v_pk_mul_f32 v[74:75], v[78:79], v[74:75]
	s_nop 0
	v_cvt_pk_bf16_f32 v74, v74, v75
	v_mul_f32_e32 v75, 0xbfb8aa3b, v80
	v_exp_f32_e32 v75, v75
	s_nop 0
	v_add_f32_e32 v75, 1.0, v75
	v_rcp_f32_e32 v78, v75
	v_mul_f32_e32 v75, 0xbfb8aa3b, v81
	v_exp_f32_e32 v75, v75
	s_nop 0
	v_add_f32_e32 v75, 1.0, v75
	v_rcp_f32_e32 v79, v75
	s_nop 0
	v_pk_mul_f32 v[78:79], v[80:81], v[78:79]
	s_nop 0
	v_pk_mul_f32 v[76:77], v[78:79], v[76:77]
	s_nop 0
	v_cvt_pk_bf16_f32 v75, v76, v77
	v_mul_f32_e32 v76, 0xbfb8aa3b, v70
	v_mul_f32_e32 v77, 0xbfb8aa3b, v71
	v_exp_f32_e32 v76, v76
	v_exp_f32_e32 v77, v77
	v_add_f32_e32 v76, 1.0, v76
	v_add_f32_e32 v77, 1.0, v77
	v_rcp_f32_e32 v76, v76
	v_rcp_f32_e32 v77, v77
	s_nop 0
	v_pk_mul_f32 v[70:71], v[70:71], v[76:77]
	s_nop 0
	v_pk_mul_f32 v[66:67], v[70:71], v[66:67]
	s_nop 0
	v_cvt_pk_bf16_f32 v76, v66, v67
	v_mul_f32_e32 v66, 0xbfb8aa3b, v72
	v_mul_f32_e32 v67, 0xbfb8aa3b, v73
	v_exp_f32_e32 v66, v66
	v_exp_f32_e32 v67, v67
	v_add_f32_e32 v66, 1.0, v66
	v_add_f32_e32 v67, 1.0, v67
	v_rcp_f32_e32 v66, v66
	v_rcp_f32_e32 v67, v67
	s_nop 0
	v_pk_mul_f32 v[66:67], v[72:73], v[66:67]
	s_nop 0
	v_pk_mul_f32 v[66:67], v[66:67], v[68:69]
	v_mul_f32_e32 v68, 0xbfb8aa3b, v62
	v_mul_f32_e32 v69, 0xbfb8aa3b, v63
	v_exp_f32_e32 v68, v68
	v_exp_f32_e32 v69, v69
	v_cvt_pk_bf16_f32 v77, v66, v67
	v_add_u32_e32 v66, 0x80, v158
	v_add_f32_e32 v68, 1.0, v68
	v_add_f32_e32 v69, 1.0, v69
	v_rcp_f32_e32 v68, v68
	v_rcp_f32_e32 v69, v69
	v_mad_i64_i32 v[66:67], s[26:27], v66, s2, v[142:143]
	v_lshl_add_u64 v[66:67], v[66:67], 0, v[144:145]
	v_pk_mul_f32 v[62:63], v[62:63], v[68:69]
	global_store_dwordx4 v[82:83], v[74:77], off sc0 sc1
	v_pk_mul_f32 v[58:59], v[62:63], v[58:59]
	s_nop 0
	v_cvt_pk_bf16_f32 v58, v58, v59
	v_mul_f32_e32 v59, 0xbfb8aa3b, v64
	v_exp_f32_e32 v59, v59
	s_nop 0
	v_add_f32_e32 v59, 1.0, v59
	v_rcp_f32_e32 v62, v59
	v_mul_f32_e32 v59, 0xbfb8aa3b, v65
; __device__ __forceinline__ unsigned cvt_pk_bf16(float lo, float hi) { const f32x2c f = {lo, hi}; return __builtin_bit_cast(unsigned, __builtin_convertvector(f, bf16x2c)); }
; __device__ __forceinline__ float silu_f(float g) { return g * __builtin_amdgcn_rcpf(1.0f + __expf(-g)); }
;     __device__ __forceinline__ void operator()(const f32x4 (&acc)[2][2][4][2], const Unit& u, int wr, int wc, int fr, int fq) const {
;         const int row0 = u.pm * BM + wr * 64 + fr; const int col0 = u.pn * HALF + wc * 32 + 8 * fq;
; #pragma unroll
;         for (int ai = 0; ai < 2; ++ai)
; #pragma unroll
;             for (int m = 0; m < 4; ++m) { bf16_t* rowp = H + (size_t)(row0 + ai * HALF + m * 16) * ldh + col0;
;                 const f32x4 g0 = acc[ai][0][m][0], g1 = acc[ai][0][m][1], u0 = acc[ai][1][m][0], u1 = acc[ai][1][m][1];
;                 u32x4 w; w.x = cvt_pk_bf16(silu_f(g0[0]) * u0[0], silu_f(g0[1]) * u0[1]); w.y = cvt_pk_bf16(silu_f(g0[2]) * u0[2], silu_f(g0[3]) * u0[3]);
;                 w.z = cvt_pk_bf16(silu_f(g1[0]) * u1[0], silu_f(g1[1]) * u1[1]); w.w = cvt_pk_bf16(silu_f(g1[2]) * u1[2], silu_f(g1[3]) * u1[3]);
;                 *(u32x4*)rowp = w; }
	v_exp_f32_e32 v59, v59
	s_nop 0
	v_add_f32_e32 v59, 1.0, v59
	v_rcp_f32_e32 v63, v59
	s_nop 0
	v_pk_mul_f32 v[62:63], v[64:65], v[62:63]
	s_nop 0
	v_pk_mul_f32 v[60:61], v[62:63], v[60:61]
	s_nop 0
	v_cvt_pk_bf16_f32 v59, v60, v61
	v_mul_f32_e32 v60, 0xbfb8aa3b, v54
	v_mul_f32_e32 v61, 0xbfb8aa3b, v55
	v_exp_f32_e32 v60, v60
	v_exp_f32_e32 v61, v61
	v_add_f32_e32 v60, 1.0, v60
	v_add_f32_e32 v61, 1.0, v61
	v_rcp_f32_e32 v60, v60
	v_rcp_f32_e32 v61, v61
	s_nop 0
	v_pk_mul_f32 v[54:55], v[54:55], v[60:61]
	s_nop 0
	v_pk_mul_f32 v[50:51], v[54:55], v[50:51]
	s_nop 0
	v_cvt_pk_bf16_f32 v60, v50, v51
	v_mul_f32_e32 v50, 0xbfb8aa3b, v56
	v_mul_f32_e32 v51, 0xbfb8aa3b, v57
	v_exp_f32_e32 v50, v50
	v_exp_f32_e32 v51, v51
	v_add_f32_e32 v50, 1.0, v50
	v_add_f32_e32 v51, 1.0, v51
	v_rcp_f32_e32 v50, v50
	v_rcp_f32_e32 v51, v51
	s_nop 0
	v_pk_mul_f32 v[50:51], v[56:57], v[50:51]
	s_nop 0
	v_pk_mul_f32 v[50:51], v[50:51], v[52:53]
	v_mul_f32_e32 v52, 0xbfb8aa3b, v46
	v_mul_f32_e32 v53, 0xbfb8aa3b, v47
	v_exp_f32_e32 v52, v52
	v_exp_f32_e32 v53, v53
	v_cvt_pk_bf16_f32 v61, v50, v51
	v_add_u32_e32 v50, 0x90, v158
	v_add_f32_e32 v52, 1.0, v52
	v_add_f32_e32 v53, 1.0, v53
	v_rcp_f32_e32 v52, v52
	v_rcp_f32_e32 v53, v53
	v_mad_i64_i32 v[50:51], s[26:27], v50, s2, v[142:143]
	v_lshl_add_u64 v[50:51], v[50:51], 0, v[144:145]
	v_pk_mul_f32 v[46:47], v[46:47], v[52:53]
	global_store_dwordx4 v[66:67], v[58:61], off sc0 sc1
	v_pk_mul_f32 v[42:43], v[46:47], v[42:43]
	s_nop 0
	v_cvt_pk_bf16_f32 v42, v42, v43
	v_mul_f32_e32 v43, 0xbfb8aa3b, v48
	v_exp_f32_e32 v43, v43
	s_nop 0
	v_add_f32_e32 v43, 1.0, v43
	v_rcp_f32_e32 v46, v43
	v_mul_f32_e32 v43, 0xbfb8aa3b, v49
	v_exp_f32_e32 v43, v43
	s_nop 0
	v_add_f32_e32 v43, 1.0, v43
	v_rcp_f32_e32 v47, v43
	s_nop 0
	v_pk_mul_f32 v[46:47], v[48:49], v[46:47]
	s_nop 0
	v_pk_mul_f32 v[44:45], v[46:47], v[44:45]
	s_nop 0
	v_cvt_pk_bf16_f32 v43, v44, v45
	v_mul_f32_e32 v44, 0xbfb8aa3b, v38
	v_mul_f32_e32 v45, 0xbfb8aa3b, v39
	v_exp_f32_e32 v44, v44
	v_exp_f32_e32 v45, v45
	v_add_f32_e32 v44, 1.0, v44
	v_add_f32_e32 v45, 1.0, v45
	v_rcp_f32_e32 v44, v44
	v_rcp_f32_e32 v45, v45
	s_nop 0
	v_pk_mul_f32 v[38:39], v[38:39], v[44:45]
	s_nop 0
	v_pk_mul_f32 v[34:35], v[38:39], v[34:35]
	s_nop 0
	v_cvt_pk_bf16_f32 v44, v34, v35
	v_mul_f32_e32 v34, 0xbfb8aa3b, v40
	v_mul_f32_e32 v35, 0xbfb8aa3b, v41
	v_exp_f32_e32 v34, v34
	v_exp_f32_e32 v35, v35
	v_add_f32_e32 v34, 1.0, v34
	v_add_f32_e32 v35, 1.0, v35
	v_rcp_f32_e32 v34, v34
	v_rcp_f32_e32 v35, v35
	s_nop 0
	v_pk_mul_f32 v[34:35], v[40:41], v[34:35]
	s_nop 0
	v_pk_mul_f32 v[34:35], v[34:35], v[36:37]
	v_mul_f32_e32 v36, 0xbfb8aa3b, v30
	v_mul_f32_e32 v37, 0xbfb8aa3b, v31
	v_exp_f32_e32 v36, v36
	v_exp_f32_e32 v37, v37
	v_cvt_pk_bf16_f32 v45, v34, v35
	v_add_u32_e32 v34, 0xa0, v158
	v_add_f32_e32 v36, 1.0, v36
	v_add_f32_e32 v37, 1.0, v37
	v_rcp_f32_e32 v36, v36
	v_rcp_f32_e32 v37, v37
	v_mad_i64_i32 v[34:35], s[26:27], v34, s2, v[142:143]
	v_lshl_add_u64 v[34:35], v[34:35], 0, v[144:145]
	v_pk_mul_f32 v[30:31], v[30:31], v[36:37]
	global_store_dwordx4 v[50:51], v[42:45], off sc0 sc1
	v_pk_mul_f32 v[26:27], v[30:31], v[26:27]
	s_nop 0
	v_cvt_pk_bf16_f32 v26, v26, v27
	v_mul_f32_e32 v27, 0xbfb8aa3b, v32
	v_exp_f32_e32 v27, v27
	s_nop 0
	v_add_f32_e32 v27, 1.0, v27
	v_rcp_f32_e32 v30, v27
	v_mul_f32_e32 v27, 0xbfb8aa3b, v33
	v_exp_f32_e32 v27, v27
	s_nop 0
	v_add_f32_e32 v27, 1.0, v27
	v_rcp_f32_e32 v31, v27
	s_nop 0
	v_pk_mul_f32 v[30:31], v[32:33], v[30:31]
	s_nop 0
	v_pk_mul_f32 v[28:29], v[30:31], v[28:29]
	s_nop 0
	v_cvt_pk_bf16_f32 v27, v28, v29
	v_mul_f32_e32 v28, 0xbfb8aa3b, v22
	v_mul_f32_e32 v29, 0xbfb8aa3b, v23
	v_exp_f32_e32 v28, v28
	v_exp_f32_e32 v29, v29
	v_add_f32_e32 v28, 1.0, v28
	v_add_f32_e32 v29, 1.0, v29
	v_rcp_f32_e32 v28, v28
	v_rcp_f32_e32 v29, v29
	s_nop 0
	v_pk_mul_f32 v[22:23], v[22:23], v[28:29]
	s_nop 0
	v_pk_mul_f32 v[18:19], v[22:23], v[18:19]
	s_nop 0
	v_cvt_pk_bf16_f32 v28, v18, v19
	v_mul_f32_e32 v18, 0xbfb8aa3b, v24
	v_mul_f32_e32 v19, 0xbfb8aa3b, v25
	v_exp_f32_e32 v18, v18
	v_exp_f32_e32 v19, v19
	v_add_f32_e32 v18, 1.0, v18
	v_add_f32_e32 v19, 1.0, v19
	v_rcp_f32_e32 v18, v18
	v_rcp_f32_e32 v19, v19
	s_nop 0
	v_pk_mul_f32 v[18:19], v[24:25], v[18:19]
	s_nop 0
	v_pk_mul_f32 v[18:19], v[18:19], v[20:21]
	v_mul_f32_e32 v20, 0xbfb8aa3b, v14
	v_mul_f32_e32 v21, 0xbfb8aa3b, v15
	v_exp_f32_e32 v20, v20
	v_exp_f32_e32 v21, v21
	v_cvt_pk_bf16_f32 v29, v18, v19
	v_add_u32_e32 v18, 0xb0, v158
	v_add_f32_e32 v20, 1.0, v20
	v_add_f32_e32 v21, 1.0, v21
	v_rcp_f32_e32 v20, v20
	v_rcp_f32_e32 v21, v21
	v_mad_i64_i32 v[18:19], s[26:27], v18, s2, v[142:143]
	v_lshl_add_u64 v[18:19], v[18:19], 0, v[144:145]
	v_pk_mul_f32 v[14:15], v[14:15], v[20:21]
	s_mov_b32 s2, s18
	v_pk_mul_f32 v[10:11], v[14:15], v[10:11]
	s_mov_b64 s[26:27], s[24:25]
	v_cvt_pk_bf16_f32 v10, v10, v11
	v_mul_f32_e32 v11, 0xbfb8aa3b, v16
	v_exp_f32_e32 v11, v11
	global_store_dwordx4 v[34:35], v[26:29], off sc0 sc1
	v_add_f32_e32 v11, 1.0, v11
	v_rcp_f32_e32 v14, v11
	v_mul_f32_e32 v11, 0xbfb8aa3b, v17
	v_exp_f32_e32 v11, v11
	s_nop 0
	v_add_f32_e32 v11, 1.0, v11
	v_rcp_f32_e32 v15, v11
	s_nop 0
	v_pk_mul_f32 v[14:15], v[16:17], v[14:15]
	s_nop 0
	v_pk_mul_f32 v[12:13], v[14:15], v[12:13]
	s_nop 0
	v_cvt_pk_bf16_f32 v11, v12, v13
	v_mul_f32_e32 v12, 0xbfb8aa3b, v6
	v_mul_f32_e32 v13, 0xbfb8aa3b, v7
	v_exp_f32_e32 v12, v12
	v_exp_f32_e32 v13, v13
	v_add_f32_e32 v12, 1.0, v12
	v_add_f32_e32 v13, 1.0, v13
	v_rcp_f32_e32 v12, v12
	v_rcp_f32_e32 v13, v13
	s_nop 0
	v_pk_mul_f32 v[6:7], v[6:7], v[12:13]
	s_nop 0
	v_pk_mul_f32 v[2:3], v[6:7], v[2:3]
	s_nop 0
	v_cvt_pk_bf16_f32 v12, v2, v3
	v_mul_f32_e32 v2, 0xbfb8aa3b, v8
	v_mul_f32_e32 v3, 0xbfb8aa3b, v9
	v_exp_f32_e32 v2, v2
	v_exp_f32_e32 v3, v3
	v_add_f32_e32 v2, 1.0, v2
	v_add_f32_e32 v3, 1.0, v3
	v_rcp_f32_e32 v2, v2
	v_rcp_f32_e32 v3, v3
	s_nop 0
	v_pk_mul_f32 v[2:3], v[8:9], v[2:3]
	s_nop 0
	v_pk_mul_f32 v[2:3], v[2:3], v[4:5]
	s_nop 0
	v_cvt_pk_bf16_f32 v13, v2, v3
	global_store_dwordx4 v[18:19], v[10:13], off sc0 sc1
	s_cbranch_vccz .LBB0_1106
	s_waitcnt vmcnt(0)
	v_readlane_b32 s12, v255, 32
	v_readlane_b32 s52, v255, 35
	v_readlane_b32 s60, v255, 37
	s_cmpk_gt_u32 s8, 0xff
	v_readlane_b32 s13, v255, 33
	v_readlane_b32 s53, v255, 36
	v_readlane_b32 s61, v255, 38
	s_cbranch_scc1 .LBB0_1113
	s_barrier
